# FFN gate/up epilogue rewritten by hand: saddr addressing with one voffset chain, row-by-row SwiGLU, stores spread, direct hsum adds (same arithmetic)
# speedup vs baseline: 1.0103x; 1.0066x over previous
; __device__ __forceinline__ unsigned cvt_pk_bf16(float lo, float hi) { const f32x2c_ v = {lo, hi}; const bf16x2c_ b = __builtin_convertvector(v, bf16x2c_); return __builtin_bit_cast(unsigned, b); }
; __device__ __forceinline__ void stat_issue(const float* ss, const Unit& u, int wr, int fr, int fq, f32x4 (&raw)[8]) {
; #pragma unroll
;     for (int ai = 0; ai < 2; ++ai)
; #pragma unroll
;         for (int m = 0; m < 4; ++m) raw[ai * 4 + m] = ((const f32x4*)(ss + (size_t)(u.pm * BM + ai * HALF + wr * 64 + m * 16 + fr) * 16))[fq];
; }
;     __device__ __forceinline__ void operator()(const f32x4 (&acc)[2][2][4][2], const Unit& u, int wr, int wc, int fr, int fq, const float (&rsv)[8]) const {
;     ...
;                 const int row = u.pm * BM + ai * HALF + wr * 64 + m * 16 + fr;
;                 const float rs = rsv[ai * 4 + m];
;                 u32x4 w;
; #pragma unroll
;                 for (int n = 0; n < 2; ++n) {
;                     const f32x4 g = acc[ai][0][m][n] * rs, up = acc[ai][1][m][n] * rs;
;                     const f32x2 g0 = {g[0], g[1]}, g1 = {g[2], g[3]}, u0 = {up[0], up[1]}, u1 = {up[2], up[3]};
;                     const f32x2 h0 = (g0 * u0) * sigmoid_pk(g0), h1 = (g1 * u1) * sigmoid_pk(g1);
;                     w[2 * n] = cvt_pk_bf16(h0.x, h0.y); w[2 * n + 1] = cvt_pk_bf16(h1.x, h1.y);
;                 }
;                 *(u32x4*)(hid + (size_t)row * ldh + u.pn * 128 + wc * 32 + 8 * fq) = w;
.LBB0_203:
	s_lshl_b32 s4, s42, 8
	v_add_u32_e32 v252, s29, v173
	v_add_u32_e32 v248, s4, v252
	v_lshlrev_b32_e32 v253, 4, v175
	v_lshl_add_u32 v248, v248, 6, v253
	v_add_u32_e32 v249, 0x2000, v248
	global_load_dwordx4 v[126:129], v248, s[74:75]
	global_load_dwordx4 v[118:121], v248, s[74:75] offset:1024
	global_load_dwordx4 v[110:113], v248, s[74:75] offset:2048
	global_load_dwordx4 v[106:109], v248, s[74:75] offset:3072
	global_load_dwordx4 v[102:105], v249, s[74:75]
	global_load_dwordx4 v[98:101], v249, s[74:75] offset:1024
	global_load_dwordx4 v[94:97], v249, s[74:75] offset:2048
	global_load_dwordx4 v[86:89], v249, s[74:75] offset:3072
	s_lshl_b32 s17, s41, 8
	s_lshl_b32 s4, s2, 8
	s_add_i32 s4, s4, s78
	v_add_u32_e32 v251, s17, v252
	v_add_u32_e32 v253, s4, v253
	v_mad_u32_u24 v250, v251, s33, v253
	v_pk_mul_f32 v[158:159], v[186:187], v[158:159] op_sel_hi:[0,1]
	v_pk_mul_f32 v[160:161], v[186:187], v[160:161] op_sel_hi:[0,1]
	v_pk_mul_f32 v[150:151], v[186:187], v[150:151] op_sel_hi:[0,1]
	v_pk_mul_f32 v[152:153], v[186:187], v[152:153] op_sel_hi:[0,1]
	v_pk_mul_f32 v[154:155], v[186:187], v[154:155] op_sel_hi:[0,1]
	v_pk_mul_f32 v[156:157], v[186:187], v[156:157] op_sel_hi:[0,1]
	v_pk_mul_f32 v[146:147], v[186:187], v[146:147] op_sel_hi:[0,1]
	v_pk_mul_f32 v[148:149], v[186:187], v[148:149] op_sel_hi:[0,1]
	v_pk_mul_f32 v[154:155], v[154:155], v[158:159]
	v_pk_mul_f32 v[156:157], v[156:157], v[160:161]
	v_pk_mul_f32 v[146:147], v[146:147], v[150:151]
	v_pk_mul_f32 v[148:149], v[148:149], v[152:153]
	v_pk_mul_f32 v[158:159], v[158:159], s[90:91] op_sel_hi:[1,0]
	v_pk_mul_f32 v[160:161], v[160:161], s[90:91] op_sel_hi:[1,0]
	v_pk_mul_f32 v[150:151], v[150:151], s[90:91] op_sel_hi:[1,0]
	v_pk_mul_f32 v[152:153], v[152:153], s[90:91] op_sel_hi:[1,0]
	v_exp_f32_e32 v158, v158
	v_exp_f32_e32 v159, v159
	v_exp_f32_e32 v160, v160
	v_exp_f32_e32 v161, v161
	v_exp_f32_e32 v150, v150
	v_exp_f32_e32 v151, v151
	v_exp_f32_e32 v152, v152
	v_exp_f32_e32 v153, v153
	v_pk_add_f32 v[158:159], v[158:159], 1.0 op_sel_hi:[1,0]
	v_pk_add_f32 v[160:161], v[160:161], 1.0 op_sel_hi:[1,0]
	v_pk_add_f32 v[150:151], v[150:151], 1.0 op_sel_hi:[1,0]
	v_pk_add_f32 v[152:153], v[152:153], 1.0 op_sel_hi:[1,0]
	v_rcp_f32_e32 v158, v158
	v_rcp_f32_e32 v159, v159
	v_rcp_f32_e32 v160, v160
	v_rcp_f32_e32 v161, v161
	v_rcp_f32_e32 v150, v150
	v_rcp_f32_e32 v151, v151
	v_rcp_f32_e32 v152, v152
	v_rcp_f32_e32 v153, v153
	v_pk_mul_f32 v[154:155], v[154:155], v[158:159]
	v_pk_mul_f32 v[156:157], v[156:157], v[160:161]
	v_pk_mul_f32 v[146:147], v[146:147], v[150:151]
	v_pk_mul_f32 v[148:149], v[148:149], v[152:153]
	v_cvt_pk_bf16_f32 v154, v154, v155
	v_cvt_pk_bf16_f32 v155, v156, v157
	v_cvt_pk_bf16_f32 v156, v146, v147
	v_cvt_pk_bf16_f32 v157, v148, v149
	global_store_dwordx4 v250, v[154:157], s[0:1]
	v_pk_mul_f32 v[142:143], v[184:185], v[142:143] op_sel_hi:[0,1]
	v_pk_mul_f32 v[144:145], v[184:185], v[144:145] op_sel_hi:[0,1]
	v_pk_mul_f32 v[134:135], v[184:185], v[134:135] op_sel_hi:[0,1]
	v_pk_mul_f32 v[136:137], v[184:185], v[136:137] op_sel_hi:[0,1]
	v_pk_mul_f32 v[138:139], v[184:185], v[138:139] op_sel_hi:[0,1]
	v_pk_mul_f32 v[140:141], v[184:185], v[140:141] op_sel_hi:[0,1]
	v_pk_mul_f32 v[130:131], v[184:185], v[130:131] op_sel_hi:[0,1]
	v_pk_mul_f32 v[132:133], v[184:185], v[132:133] op_sel_hi:[0,1]
	v_pk_mul_f32 v[138:139], v[138:139], v[142:143]
	v_pk_mul_f32 v[140:141], v[140:141], v[144:145]
	v_pk_mul_f32 v[130:131], v[130:131], v[134:135]
	v_pk_mul_f32 v[132:133], v[132:133], v[136:137]
	v_pk_mul_f32 v[142:143], v[142:143], s[90:91] op_sel_hi:[1,0]
	v_pk_mul_f32 v[144:145], v[144:145], s[90:91] op_sel_hi:[1,0]
	v_pk_mul_f32 v[134:135], v[134:135], s[90:91] op_sel_hi:[1,0]
	v_pk_mul_f32 v[136:137], v[136:137], s[90:91] op_sel_hi:[1,0]
	v_exp_f32_e32 v142, v142
	v_exp_f32_e32 v143, v143
	v_exp_f32_e32 v144, v144
	v_exp_f32_e32 v145, v145
	v_exp_f32_e32 v134, v134
	v_exp_f32_e32 v135, v135
	v_exp_f32_e32 v136, v136
	v_exp_f32_e32 v137, v137
	v_pk_add_f32 v[142:143], v[142:143], 1.0 op_sel_hi:[1,0]
	v_pk_add_f32 v[144:145], v[144:145], 1.0 op_sel_hi:[1,0]
	v_pk_add_f32 v[134:135], v[134:135], 1.0 op_sel_hi:[1,0]
	v_pk_add_f32 v[136:137], v[136:137], 1.0 op_sel_hi:[1,0]
	v_rcp_f32_e32 v142, v142
	v_rcp_f32_e32 v143, v143
	v_rcp_f32_e32 v144, v144
	v_rcp_f32_e32 v145, v145
	v_rcp_f32_e32 v134, v134
	v_rcp_f32_e32 v135, v135
	v_rcp_f32_e32 v136, v136
	v_rcp_f32_e32 v137, v137
	v_pk_mul_f32 v[138:139], v[138:139], v[142:143]
	v_pk_mul_f32 v[140:141], v[140:141], v[144:145]
	v_pk_mul_f32 v[130:131], v[130:131], v[134:135]
	v_pk_mul_f32 v[132:133], v[132:133], v[136:137]
	v_add_u32_e32 v250, 0x16000, v250
	v_cvt_pk_bf16_f32 v138, v138, v139
	v_cvt_pk_bf16_f32 v139, v140, v141
	v_cvt_pk_bf16_f32 v140, v130, v131
	v_cvt_pk_bf16_f32 v141, v132, v133
	global_store_dwordx4 v250, v[138:141], s[0:1]
	v_pk_mul_f32 v[122:123], v[182:183], v[122:123] op_sel_hi:[0,1]
	v_pk_mul_f32 v[124:125], v[182:183], v[124:125] op_sel_hi:[0,1]
	v_pk_mul_f32 v[90:91], v[182:183], v[90:91] op_sel_hi:[0,1]
	v_pk_mul_f32 v[92:93], v[182:183], v[92:93] op_sel_hi:[0,1]
	v_pk_mul_f32 v[114:115], v[182:183], v[114:115] op_sel_hi:[0,1]
	v_pk_mul_f32 v[116:117], v[182:183], v[116:117] op_sel_hi:[0,1]
	v_pk_mul_f32 v[82:83], v[182:183], v[82:83] op_sel_hi:[0,1]
	v_pk_mul_f32 v[84:85], v[182:183], v[84:85] op_sel_hi:[0,1]
	v_pk_mul_f32 v[114:115], v[114:115], v[122:123]
	v_pk_mul_f32 v[116:117], v[116:117], v[124:125]
	v_pk_mul_f32 v[82:83], v[82:83], v[90:91]
	v_pk_mul_f32 v[84:85], v[84:85], v[92:93]
	v_pk_mul_f32 v[122:123], v[122:123], s[90:91] op_sel_hi:[1,0]
	v_pk_mul_f32 v[124:125], v[124:125], s[90:91] op_sel_hi:[1,0]
; __device__ __forceinline__ unsigned cvt_pk_bf16(float lo, float hi) { const f32x2c_ v = {lo, hi}; const bf16x2c_ b = __builtin_convertvector(v, bf16x2c_); return __builtin_bit_cast(unsigned, b); }
;     __device__ __forceinline__ void operator()(const f32x4 (&acc)[2][2][4][2], const Unit& u, int wr, int wc, int fr, int fq, const float (&rsv)[8]) const {
;     ...
;                 const int row = u.pm * BM + ai * HALF + wr * 64 + m * 16 + fr;
;                 const float rs = rsv[ai * 4 + m];
;                 u32x4 w;
; #pragma unroll
;                 for (int n = 0; n < 2; ++n) {
;                     const f32x4 g = acc[ai][0][m][n] * rs, up = acc[ai][1][m][n] * rs;
;                     const f32x2 g0 = {g[0], g[1]}, g1 = {g[2], g[3]}, u0 = {up[0], up[1]}, u1 = {up[2], up[3]};
;                     const f32x2 h0 = (g0 * u0) * sigmoid_pk(g0), h1 = (g1 * u1) * sigmoid_pk(g1);
;                     w[2 * n] = cvt_pk_bf16(h0.x, h0.y); w[2 * n + 1] = cvt_pk_bf16(h1.x, h1.y);
;                 }
;                 *(u32x4*)(hid + (size_t)row * ldh + u.pn * 128 + wc * 32 + 8 * fq) = w;
	v_pk_mul_f32 v[90:91], v[90:91], s[90:91] op_sel_hi:[1,0]
	v_pk_mul_f32 v[92:93], v[92:93], s[90:91] op_sel_hi:[1,0]
	v_exp_f32_e32 v122, v122
	v_exp_f32_e32 v123, v123
	v_exp_f32_e32 v124, v124
	v_exp_f32_e32 v125, v125
	v_exp_f32_e32 v90, v90
	v_exp_f32_e32 v91, v91
	v_exp_f32_e32 v92, v92
	v_exp_f32_e32 v93, v93
	v_pk_add_f32 v[122:123], v[122:123], 1.0 op_sel_hi:[1,0]
	v_pk_add_f32 v[124:125], v[124:125], 1.0 op_sel_hi:[1,0]
	v_pk_add_f32 v[90:91], v[90:91], 1.0 op_sel_hi:[1,0]
	v_pk_add_f32 v[92:93], v[92:93], 1.0 op_sel_hi:[1,0]
	v_rcp_f32_e32 v122, v122
	v_rcp_f32_e32 v123, v123
	v_rcp_f32_e32 v124, v124
	v_rcp_f32_e32 v125, v125
	v_rcp_f32_e32 v90, v90
	v_rcp_f32_e32 v91, v91
	v_rcp_f32_e32 v92, v92
	v_rcp_f32_e32 v93, v93
	v_pk_mul_f32 v[114:115], v[114:115], v[122:123]
	v_pk_mul_f32 v[116:117], v[116:117], v[124:125]
	v_pk_mul_f32 v[82:83], v[82:83], v[90:91]
	v_pk_mul_f32 v[84:85], v[84:85], v[92:93]
	v_add_u32_e32 v250, 0x16000, v250
	v_cvt_pk_bf16_f32 v114, v114, v115
	v_cvt_pk_bf16_f32 v115, v116, v117
	v_cvt_pk_bf16_f32 v116, v82, v83
	v_cvt_pk_bf16_f32 v117, v84, v85
	global_store_dwordx4 v250, v[114:117], s[0:1]
	v_pk_mul_f32 v[78:79], v[180:181], v[78:79] op_sel_hi:[0,1]
	v_pk_mul_f32 v[80:81], v[180:181], v[80:81] op_sel_hi:[0,1]
	v_pk_mul_f32 v[70:71], v[180:181], v[70:71] op_sel_hi:[0,1]
	v_pk_mul_f32 v[72:73], v[180:181], v[72:73] op_sel_hi:[0,1]
	v_pk_mul_f32 v[74:75], v[180:181], v[74:75] op_sel_hi:[0,1]
	v_pk_mul_f32 v[76:77], v[180:181], v[76:77] op_sel_hi:[0,1]
	v_pk_mul_f32 v[66:67], v[180:181], v[66:67] op_sel_hi:[0,1]
	v_pk_mul_f32 v[68:69], v[180:181], v[68:69] op_sel_hi:[0,1]
	v_pk_mul_f32 v[74:75], v[74:75], v[78:79]
	v_pk_mul_f32 v[76:77], v[76:77], v[80:81]
	v_pk_mul_f32 v[66:67], v[66:67], v[70:71]
	v_pk_mul_f32 v[68:69], v[68:69], v[72:73]
	v_pk_mul_f32 v[78:79], v[78:79], s[90:91] op_sel_hi:[1,0]
	v_pk_mul_f32 v[80:81], v[80:81], s[90:91] op_sel_hi:[1,0]
	v_pk_mul_f32 v[70:71], v[70:71], s[90:91] op_sel_hi:[1,0]
	v_pk_mul_f32 v[72:73], v[72:73], s[90:91] op_sel_hi:[1,0]
	v_exp_f32_e32 v78, v78
	v_exp_f32_e32 v79, v79
	v_exp_f32_e32 v80, v80
	v_exp_f32_e32 v81, v81
	v_exp_f32_e32 v70, v70
	v_exp_f32_e32 v71, v71
	v_exp_f32_e32 v72, v72
	v_exp_f32_e32 v73, v73
	v_pk_add_f32 v[78:79], v[78:79], 1.0 op_sel_hi:[1,0]
	v_pk_add_f32 v[80:81], v[80:81], 1.0 op_sel_hi:[1,0]
	v_pk_add_f32 v[70:71], v[70:71], 1.0 op_sel_hi:[1,0]
	v_pk_add_f32 v[72:73], v[72:73], 1.0 op_sel_hi:[1,0]
	v_rcp_f32_e32 v78, v78
	v_rcp_f32_e32 v79, v79
	v_rcp_f32_e32 v80, v80
	v_rcp_f32_e32 v81, v81
	v_rcp_f32_e32 v70, v70
	v_rcp_f32_e32 v71, v71
	v_rcp_f32_e32 v72, v72
	v_rcp_f32_e32 v73, v73
	v_pk_mul_f32 v[74:75], v[74:75], v[78:79]
	v_pk_mul_f32 v[76:77], v[76:77], v[80:81]
	v_pk_mul_f32 v[66:67], v[66:67], v[70:71]
	v_pk_mul_f32 v[68:69], v[68:69], v[72:73]
	v_add_u32_e32 v250, 0x16000, v250
	v_cvt_pk_bf16_f32 v74, v74, v75
	v_cvt_pk_bf16_f32 v75, v76, v77
	v_cvt_pk_bf16_f32 v76, v66, v67
	v_cvt_pk_bf16_f32 v77, v68, v69
	global_store_dwordx4 v250, v[74:77], s[0:1]
	v_pk_mul_f32 v[60:61], v[178:179], v[60:61] op_sel_hi:[0,1]
	v_pk_mul_f32 v[62:63], v[178:179], v[62:63] op_sel_hi:[0,1]
	v_pk_mul_f32 v[52:53], v[178:179], v[52:53] op_sel_hi:[0,1]
	v_pk_mul_f32 v[54:55], v[178:179], v[54:55] op_sel_hi:[0,1]
	v_pk_mul_f32 v[56:57], v[178:179], v[56:57] op_sel_hi:[0,1]
	v_pk_mul_f32 v[58:59], v[178:179], v[58:59] op_sel_hi:[0,1]
	v_pk_mul_f32 v[48:49], v[178:179], v[48:49] op_sel_hi:[0,1]
	v_pk_mul_f32 v[50:51], v[178:179], v[50:51] op_sel_hi:[0,1]
	v_pk_mul_f32 v[56:57], v[56:57], v[60:61]
	v_pk_mul_f32 v[58:59], v[58:59], v[62:63]
	v_pk_mul_f32 v[48:49], v[48:49], v[52:53]
	v_pk_mul_f32 v[50:51], v[50:51], v[54:55]
	v_pk_mul_f32 v[60:61], v[60:61], s[90:91] op_sel_hi:[1,0]
	v_pk_mul_f32 v[62:63], v[62:63], s[90:91] op_sel_hi:[1,0]
	v_pk_mul_f32 v[52:53], v[52:53], s[90:91] op_sel_hi:[1,0]
	v_pk_mul_f32 v[54:55], v[54:55], s[90:91] op_sel_hi:[1,0]
	v_exp_f32_e32 v60, v60
	v_exp_f32_e32 v61, v61
	v_exp_f32_e32 v62, v62
	v_exp_f32_e32 v63, v63
	v_exp_f32_e32 v52, v52
	v_exp_f32_e32 v53, v53
	v_exp_f32_e32 v54, v54
	v_exp_f32_e32 v55, v55
	v_pk_add_f32 v[60:61], v[60:61], 1.0 op_sel_hi:[1,0]
	v_pk_add_f32 v[62:63], v[62:63], 1.0 op_sel_hi:[1,0]
	v_pk_add_f32 v[52:53], v[52:53], 1.0 op_sel_hi:[1,0]
	v_pk_add_f32 v[54:55], v[54:55], 1.0 op_sel_hi:[1,0]
	v_rcp_f32_e32 v60, v60
	v_rcp_f32_e32 v61, v61
	v_rcp_f32_e32 v62, v62
	v_rcp_f32_e32 v63, v63
	v_rcp_f32_e32 v52, v52
	v_rcp_f32_e32 v53, v53
	v_rcp_f32_e32 v54, v54
	v_rcp_f32_e32 v55, v55
	v_pk_mul_f32 v[56:57], v[56:57], v[60:61]
	v_pk_mul_f32 v[58:59], v[58:59], v[62:63]
	v_pk_mul_f32 v[48:49], v[48:49], v[52:53]
	v_pk_mul_f32 v[50:51], v[50:51], v[54:55]
	v_add_u32_e32 v250, 0x6e000, v250
	v_cvt_pk_bf16_f32 v56, v56, v57
	v_cvt_pk_bf16_f32 v57, v58, v59
	v_cvt_pk_bf16_f32 v58, v48, v49
	v_cvt_pk_bf16_f32 v59, v50, v51
	global_store_dwordx4 v250, v[56:59], s[0:1]
	v_pk_mul_f32 v[44:45], v[176:177], v[44:45] op_sel_hi:[0,1]
	v_pk_mul_f32 v[46:47], v[176:177], v[46:47] op_sel_hi:[0,1]
	v_pk_mul_f32 v[36:37], v[176:177], v[36:37] op_sel_hi:[0,1]
	v_pk_mul_f32 v[38:39], v[176:177], v[38:39] op_sel_hi:[0,1]
	v_pk_mul_f32 v[40:41], v[176:177], v[40:41] op_sel_hi:[0,1]
	v_pk_mul_f32 v[42:43], v[176:177], v[42:43] op_sel_hi:[0,1]
	v_pk_mul_f32 v[32:33], v[176:177], v[32:33] op_sel_hi:[0,1]
	v_pk_mul_f32 v[34:35], v[176:177], v[34:35] op_sel_hi:[0,1]
	v_pk_mul_f32 v[40:41], v[40:41], v[44:45]
	v_pk_mul_f32 v[42:43], v[42:43], v[46:47]
	v_pk_mul_f32 v[32:33], v[32:33], v[36:37]
	v_pk_mul_f32 v[34:35], v[34:35], v[38:39]
	v_pk_mul_f32 v[44:45], v[44:45], s[90:91] op_sel_hi:[1,0]
; __device__ __forceinline__ unsigned cvt_pk_bf16(float lo, float hi) { const f32x2c_ v = {lo, hi}; const bf16x2c_ b = __builtin_convertvector(v, bf16x2c_); return __builtin_bit_cast(unsigned, b); }
; template <int N> __device__ __forceinline__ float sxor(float v) { static_assert(N > 0 && N < 32, "sxor"); return __int_as_float(__builtin_amdgcn_ds_swizzle(__float_as_int(v), 0x1f | (N << 10))); }
; __device__ __forceinline__ float sum32(float v) { const auto rr = __builtin_amdgcn_permlane32_swap(__float_as_uint(v), __float_as_uint(v), false, false); return __uint_as_float(rr[0]) + __uint_as_float(rr[1]); }
; __device__ __forceinline__ float hsum4(f32x4 a) { return (a[0] + a[1]) + (a[2] + a[3]); }
; __device__ __forceinline__ void stat_finish(const f32x4 (&raw)[8], float (&rs)[8], float invn) {
; #pragma unroll
;     for (int r = 0; r < 8; ++r) { float s = hsum4(raw[r]); s += sxor<16>(s); s = sum32(s); rs[r] = __builtin_amdgcn_rsqf(s * invn + EPS); }
; }
;     __device__ __forceinline__ void operator()(const f32x4 (&acc)[2][2][4][2], const Unit& u, int wr, int wc, int fr, int fq, const float (&rsv)[8]) const {
;     ...
;                 const int row = u.pm * BM + ai * HALF + wr * 64 + m * 16 + fr;
;                 const float rs = rsv[ai * 4 + m];
;                 u32x4 w;
; #pragma unroll
;                 for (int n = 0; n < 2; ++n) {
;                     const f32x4 g = acc[ai][0][m][n] * rs, up = acc[ai][1][m][n] * rs;
;                     const f32x2 g0 = {g[0], g[1]}, g1 = {g[2], g[3]}, u0 = {up[0], up[1]}, u1 = {up[2], up[3]};
;                     const f32x2 h0 = (g0 * u0) * sigmoid_pk(g0), h1 = (g1 * u1) * sigmoid_pk(g1);
;                     w[2 * n] = cvt_pk_bf16(h0.x, h0.y); w[2 * n + 1] = cvt_pk_bf16(h1.x, h1.y);
;                 }
;                 *(u32x4*)(hid + (size_t)row * ldh + u.pn * 128 + wc * 32 + 8 * fq) = w;
	v_pk_mul_f32 v[46:47], v[46:47], s[90:91] op_sel_hi:[1,0]
	v_pk_mul_f32 v[36:37], v[36:37], s[90:91] op_sel_hi:[1,0]
	v_pk_mul_f32 v[38:39], v[38:39], s[90:91] op_sel_hi:[1,0]
	v_exp_f32_e32 v44, v44
	v_exp_f32_e32 v45, v45
	v_exp_f32_e32 v46, v46
	v_exp_f32_e32 v47, v47
	v_exp_f32_e32 v36, v36
	v_exp_f32_e32 v37, v37
	v_exp_f32_e32 v38, v38
	v_exp_f32_e32 v39, v39
	v_pk_add_f32 v[44:45], v[44:45], 1.0 op_sel_hi:[1,0]
	v_pk_add_f32 v[46:47], v[46:47], 1.0 op_sel_hi:[1,0]
	v_pk_add_f32 v[36:37], v[36:37], 1.0 op_sel_hi:[1,0]
	v_pk_add_f32 v[38:39], v[38:39], 1.0 op_sel_hi:[1,0]
	v_rcp_f32_e32 v44, v44
	v_rcp_f32_e32 v45, v45
	v_rcp_f32_e32 v46, v46
	v_rcp_f32_e32 v47, v47
	v_rcp_f32_e32 v36, v36
	v_rcp_f32_e32 v37, v37
	v_rcp_f32_e32 v38, v38
	v_rcp_f32_e32 v39, v39
	v_pk_mul_f32 v[40:41], v[40:41], v[44:45]
	v_pk_mul_f32 v[42:43], v[42:43], v[46:47]
	v_pk_mul_f32 v[32:33], v[32:33], v[36:37]
	v_pk_mul_f32 v[34:35], v[34:35], v[38:39]
	v_add_u32_e32 v250, 0x16000, v250
	v_cvt_pk_bf16_f32 v40, v40, v41
	v_cvt_pk_bf16_f32 v41, v42, v43
	v_cvt_pk_bf16_f32 v42, v32, v33
	v_cvt_pk_bf16_f32 v43, v34, v35
	global_store_dwordx4 v250, v[40:43], s[0:1]
	v_pk_mul_f32 v[28:29], v[174:175], v[28:29] op_sel_hi:[0,1]
	v_pk_mul_f32 v[30:31], v[174:175], v[30:31] op_sel_hi:[0,1]
	v_pk_mul_f32 v[20:21], v[174:175], v[20:21] op_sel_hi:[0,1]
	v_pk_mul_f32 v[22:23], v[174:175], v[22:23] op_sel_hi:[0,1]
	v_pk_mul_f32 v[24:25], v[174:175], v[24:25] op_sel_hi:[0,1]
	v_pk_mul_f32 v[26:27], v[174:175], v[26:27] op_sel_hi:[0,1]
	v_pk_mul_f32 v[16:17], v[174:175], v[16:17] op_sel_hi:[0,1]
	v_pk_mul_f32 v[18:19], v[174:175], v[18:19] op_sel_hi:[0,1]
	v_pk_mul_f32 v[24:25], v[24:25], v[28:29]
	v_pk_mul_f32 v[26:27], v[26:27], v[30:31]
	v_pk_mul_f32 v[16:17], v[16:17], v[20:21]
	v_pk_mul_f32 v[18:19], v[18:19], v[22:23]
	v_pk_mul_f32 v[28:29], v[28:29], s[90:91] op_sel_hi:[1,0]
	v_pk_mul_f32 v[30:31], v[30:31], s[90:91] op_sel_hi:[1,0]
	v_pk_mul_f32 v[20:21], v[20:21], s[90:91] op_sel_hi:[1,0]
	v_pk_mul_f32 v[22:23], v[22:23], s[90:91] op_sel_hi:[1,0]
	v_exp_f32_e32 v28, v28
	v_exp_f32_e32 v29, v29
	v_exp_f32_e32 v30, v30
	v_exp_f32_e32 v31, v31
	v_exp_f32_e32 v20, v20
	v_exp_f32_e32 v21, v21
	v_exp_f32_e32 v22, v22
	v_exp_f32_e32 v23, v23
	v_pk_add_f32 v[28:29], v[28:29], 1.0 op_sel_hi:[1,0]
	v_pk_add_f32 v[30:31], v[30:31], 1.0 op_sel_hi:[1,0]
	v_pk_add_f32 v[20:21], v[20:21], 1.0 op_sel_hi:[1,0]
	v_pk_add_f32 v[22:23], v[22:23], 1.0 op_sel_hi:[1,0]
	v_rcp_f32_e32 v28, v28
	v_rcp_f32_e32 v29, v29
	v_rcp_f32_e32 v30, v30
	v_rcp_f32_e32 v31, v31
	v_rcp_f32_e32 v20, v20
	v_rcp_f32_e32 v21, v21
	v_rcp_f32_e32 v22, v22
	v_rcp_f32_e32 v23, v23
	v_pk_mul_f32 v[24:25], v[24:25], v[28:29]
	v_pk_mul_f32 v[26:27], v[26:27], v[30:31]
	v_pk_mul_f32 v[16:17], v[16:17], v[20:21]
	v_pk_mul_f32 v[18:19], v[18:19], v[22:23]
	v_add_u32_e32 v250, 0x16000, v250
	v_cvt_pk_bf16_f32 v24, v24, v25
	v_cvt_pk_bf16_f32 v25, v26, v27
	v_cvt_pk_bf16_f32 v26, v16, v17
	v_cvt_pk_bf16_f32 v27, v18, v19
	global_store_dwordx4 v250, v[24:27], s[0:1]
	v_pk_mul_f32 v[12:13], v[172:173], v[12:13] op_sel_hi:[0,1]
	v_pk_mul_f32 v[14:15], v[172:173], v[14:15] op_sel_hi:[0,1]
	v_pk_mul_f32 v[4:5], v[172:173], v[4:5] op_sel_hi:[0,1]
	v_pk_mul_f32 v[6:7], v[172:173], v[6:7] op_sel_hi:[0,1]
	v_pk_mul_f32 v[8:9], v[172:173], v[8:9] op_sel_hi:[0,1]
	v_pk_mul_f32 v[10:11], v[172:173], v[10:11] op_sel_hi:[0,1]
	v_pk_mul_f32 v[0:1], v[172:173], v[0:1] op_sel_hi:[0,1]
	v_pk_mul_f32 v[2:3], v[172:173], v[2:3] op_sel_hi:[0,1]
	v_pk_mul_f32 v[8:9], v[8:9], v[12:13]
	v_pk_mul_f32 v[10:11], v[10:11], v[14:15]
	v_pk_mul_f32 v[0:1], v[0:1], v[4:5]
	v_pk_mul_f32 v[2:3], v[2:3], v[6:7]
	v_pk_mul_f32 v[12:13], v[12:13], s[90:91] op_sel_hi:[1,0]
	v_pk_mul_f32 v[14:15], v[14:15], s[90:91] op_sel_hi:[1,0]
	v_pk_mul_f32 v[4:5], v[4:5], s[90:91] op_sel_hi:[1,0]
	v_pk_mul_f32 v[6:7], v[6:7], s[90:91] op_sel_hi:[1,0]
	v_exp_f32_e32 v12, v12
	v_exp_f32_e32 v13, v13
	v_exp_f32_e32 v14, v14
	v_exp_f32_e32 v15, v15
	v_exp_f32_e32 v4, v4
	v_exp_f32_e32 v5, v5
	v_exp_f32_e32 v6, v6
	v_exp_f32_e32 v7, v7
	v_pk_add_f32 v[12:13], v[12:13], 1.0 op_sel_hi:[1,0]
	v_pk_add_f32 v[14:15], v[14:15], 1.0 op_sel_hi:[1,0]
	v_pk_add_f32 v[4:5], v[4:5], 1.0 op_sel_hi:[1,0]
	v_pk_add_f32 v[6:7], v[6:7], 1.0 op_sel_hi:[1,0]
	v_rcp_f32_e32 v12, v12
	v_rcp_f32_e32 v13, v13
	v_rcp_f32_e32 v14, v14
	v_rcp_f32_e32 v15, v15
	v_rcp_f32_e32 v4, v4
	v_rcp_f32_e32 v5, v5
	v_rcp_f32_e32 v6, v6
	v_rcp_f32_e32 v7, v7
	v_pk_mul_f32 v[8:9], v[8:9], v[12:13]
	v_pk_mul_f32 v[10:11], v[10:11], v[14:15]
	v_pk_mul_f32 v[0:1], v[0:1], v[4:5]
	v_pk_mul_f32 v[2:3], v[2:3], v[6:7]
	v_add_u32_e32 v250, 0x16000, v250
	v_cvt_pk_bf16_f32 v8, v8, v9
	v_cvt_pk_bf16_f32 v9, v10, v11
	v_cvt_pk_bf16_f32 v10, v0, v1
	v_cvt_pk_bf16_f32 v11, v2, v3
	global_store_dwordx4 v250, v[8:11], s[0:1]
	s_waitcnt vmcnt(8)
	v_add_f32_e32 v0, v126, v127
	v_add_f32_e32 v1, v128, v129
	v_add_f32_e32 v2, v118, v119
	v_add_f32_e32 v3, v120, v121
	v_add_f32_e32 v4, v110, v111
	v_add_f32_e32 v5, v112, v113
	v_add_f32_e32 v6, v106, v107
	v_add_f32_e32 v7, v108, v109
	v_add_f32_e32 v8, v102, v103
	v_add_f32_e32 v9, v104, v105
	v_add_f32_e32 v10, v98, v99
	v_add_f32_e32 v11, v100, v101
	v_add_f32_e32 v12, v94, v95
	v_add_f32_e32 v13, v96, v97
	v_add_f32_e32 v14, v86, v87
	v_add_f32_e32 v15, v88, v89
	v_add_f32_e32 v0, v0, v1
	v_add_f32_e32 v2, v2, v3
	v_add_f32_e32 v4, v4, v5
	v_add_f32_e32 v6, v6, v7
	v_add_f32_e32 v8, v8, v9
	v_add_f32_e32 v10, v10, v11
	v_add_f32_e32 v12, v12, v13
	v_add_f32_e32 v14, v14, v15
	ds_swizzle_b32 v1, v0 offset:swizzle(SWAP,16)
	ds_swizzle_b32 v3, v2 offset:swizzle(SWAP,16)
	ds_swizzle_b32 v5, v4 offset:swizzle(SWAP,16)
	ds_swizzle_b32 v7, v6 offset:swizzle(SWAP,16)
	ds_swizzle_b32 v9, v8 offset:swizzle(SWAP,16)
	ds_swizzle_b32 v11, v10 offset:swizzle(SWAP,16)
	ds_swizzle_b32 v13, v12 offset:swizzle(SWAP,16)
	ds_swizzle_b32 v15, v14 offset:swizzle(SWAP,16)
	s_waitcnt lgkmcnt(0)
	v_add_f32_e32 v0, v0, v1
	v_add_f32_e32 v2, v2, v3
	v_add_f32_e32 v4, v4, v5
	v_add_f32_e32 v6, v6, v7
	v_add_f32_e32 v8, v8, v9
	v_add_f32_e32 v10, v10, v11
	v_add_f32_e32 v12, v12, v13
	v_add_f32_e32 v14, v14, v15
	v_mov_b32_e32 v1, v0
	v_mov_b32_e32 v3, v2
	v_mov_b32_e32 v5, v4
	v_mov_b32_e32 v7, v6
	v_mov_b32_e32 v9, v8
	v_mov_b32_e32 v11, v10
	v_mov_b32_e32 v13, v12
	v_mov_b32_e32 v15, v14
	v_permlane32_swap_b32_e32 v0, v1
	v_permlane32_swap_b32_e32 v2, v3
	v_permlane32_swap_b32_e32 v4, v5
	v_permlane32_swap_b32_e32 v6, v7
	v_permlane32_swap_b32_e32 v8, v9
	v_permlane32_swap_b32_e32 v10, v11
	v_permlane32_swap_b32_e32 v12, v13
	v_permlane32_swap_b32_e32 v14, v15
	s_mov_b64 s[4:5], -1
	s_andn2_b64 vcc, exec, s[6:7]
	s_cbranch_vccnz .LBB0_195
	s_andn2_b64 vcc, exec, s[10:11]
	s_cbranch_vccnz .LBB0_194
	s_barrier
	s_branch .LBB0_194
